# C + all eight GEMM K-loop heads padded to byte phase 0 mod 128 (code placement scan)
# baseline (speedup 1.0000x reference)
; #define PG8_STAGE(bufoff, gbase, voff) do { _Pragma("unroll") for (int _i = 0; _i < 2; ++_i) \
;         __builtin_amdgcn_global_load_lds((const unsigned*)((const char*)(gbase) + (voff)[_i]), (PG8_LAS unsigned*)(lds + (bufoff) + ldsw + _i * 8192), 16, 0, 0); } while (0)
; #define PG8_WAIT_V(n) asm volatile("s_waitcnt vmcnt(" #n ")" ::: "memory")
; #define PG8_BAR __builtin_amdgcn_s_barrier()
; template <class Epi, class Sched, bool ALIGN_EPI = false, bool SP2 = false, bool MIDHOOK = false>
; __device__ __forceinline__ void gemm_phase(PG8_LAS unsigned char* lds, const Gemm g, const Sched& S, const Epi& E) {
;     ...
;     f32x4 acc[2][2][4][2];
; #pragma unroll
;     for (int a = 0; a < 2; ++a)
; #pragma unroll
;         for (int b = 0; b < 2; ++b)
; #pragma unroll
;             for (int m = 0; m < 4; ++m)
; #pragma unroll
;                 for (int n = 0; n < 2; ++n) acc[a][b][m][n] = (f32x4){0.f, 0.f, 0.f, 0.f};
;     bf16x8 At[4][2], B0[2][2], B1[2][2];
;     const char* cA = (const char*)g.A + (size_t)cur.pm * tstep; const char* cB = (const char*)g.Bt + (size_t)cur.pn * tstep;
;     S.a_ready(cur);
;     if constexpr (SP2) {
;         PG8_STAGE(PG8_SB(0, 0), cB, voffB); PG8_STAGE(PG8_SB(0, 1), cB + hstep, voffB); PG8_STAGE(PG8_SA(0, 0), cA, voffA); PG8_STAGE(PG8_SA(0, 1), cA + hstep, voffA);
;         if (wr == 1) PG8_BAR;
;         PG8_WAIT_V(2); PG8_BAR;
;         PG8_STAGE(PG8_SB(1, 0), cB + kstep, voffB); PG8_STAGE(PG8_SA(1, 0), cA + kstep, voffA); PG8_STAGE(PG8_SB(1, 1), cB + hstep + kstep, voffB);
;         PG8_WAIT_V(6); PG8_BAR;
;     } else {
;         PG8_STAGE(PG8_SB(0, 0), cB, voffB); PG8_STAGE(PG8_SA(0, 0), cA, voffA); PG8_STAGE(PG8_SB(0, 1), cB + hstep, voffB); PG8_STAGE(PG8_SA(0, 1), cA + hstep, voffA);
;         if (wr == 1) PG8_BAR;
;         PG8_WAIT_V(4); PG8_BAR;
;         PG8_STAGE(PG8_SB(1, 0), cB + kstep, voffB); PG8_STAGE(PG8_SA(1, 0), cA + kstep, voffA); PG8_STAGE(PG8_SB(1, 1), cB + hstep + kstep, voffB);
;         PG8_WAIT_V(6); PG8_BAR;
;     }
.LBB0_373:
	v_and_b32_e32 v15, 15, v76
	v_and_b32_e32 v12, 0xfffffc00, v12
	v_lshl_or_b32 v77, s8, 6, v15
	v_lshl_add_u32 v17, s8, 13, v12
	s_mov_b64 s[8:9], 0x80
	s_add_i32 m0, s1, 0x18000
	v_lshl_add_u64 v[6:7], v[6:7], 0, s[8:9]
	s_and_b32 s39, s84, 3
	s_waitcnt vmcnt(2)
	s_barrier
	global_load_lds_dwordx4 v[6:7], off
	v_lshl_add_u64 v[4:5], v[4:5], 0, s[8:9]
	s_add_i32 m0, s1, 0x1a000
	s_add_i32 s42, s1, 0x8000
	s_add_i32 s43, s1, 0xa000
	global_load_lds_dwordx4 v[4:5], off
	v_lshl_add_u64 v[2:3], v[2:3], 0, s[8:9]
	s_mov_b32 m0, s42
	s_add_u32 s34, s4, 0x40080
	global_load_lds_dwordx4 v[2:3], off
	v_lshl_add_u64 v[0:1], v[0:1], 0, s[8:9]
	s_mov_b32 m0, s43
	s_addc_u32 s35, s5, 0
	s_add_i32 s44, s1, 0x1c000
	global_load_lds_dwordx4 v[0:1], off
	v_lshl_add_u64 v[0:1], s[34:35], 0, v[68:69]
	s_mov_b32 m0, s44
	s_add_i32 s45, s1, 0x1e000
	global_load_lds_dwordx4 v[0:1], off
	v_lshl_add_u64 v[0:1], s[34:35], 0, v[64:65]
	s_mov_b32 m0, s45
	s_add_u32 s24, s24, s28
	global_load_lds_dwordx4 v[0:1], off
	v_lshlrev_b32_e32 v0, 14, v11
	v_and_b32_e32 v0, 0xffff8000, v0
	s_addc_u32 s25, s25, 0
	v_lshl_add_u32 v0, v13, 11, v0
	v_and_b32_e32 v1, 1, v11
	s_add_u32 s24, s82, s24
	v_lshl_or_b32 v0, v1, 6, v0
	s_addc_u32 s25, s83, s25
	v_lshl_add_u32 v0, v14, 1, v0
	v_mov_b32_e32 v1, v69
	v_lshl_add_u64 v[0:1], s[24:25], 0, v[0:1]
	s_mov_b64 s[34:35], 0x17040080
	v_lshl_add_u64 v[72:73], v[0:1], 0, s[34:35]
	v_lshlrev_b32_e32 v0, 14, v8
	v_and_b32_e32 v16, 48, v76
	v_and_b32_e32 v0, 0xffff8000, v0
	v_lshl_or_b32 v15, v15, 6, v16
	v_lshlrev_b32_e32 v16, 2, v76
	v_lshl_add_u32 v0, v9, 11, v0
	v_and_b32_e32 v1, 1, v8
	v_and_b32_e32 v16, 32, v16
	v_lshl_add_u32 v12, s39, 12, v12
	v_lshl_or_b32 v0, v1, 6, v0
	s_add_u32 s46, s82, s28
	v_bitop3_b32 v12, v15, v12, v16 bitop3:0xde
	s_waitcnt vmcnt(6)
	v_lshl_add_u32 v0, v10, 1, v0
	v_mov_b32_e32 v1, v69
	s_addc_u32 s47, s83, 0
	s_add_i32 s51, 0, 0x10000
	s_add_i32 s53, 0, 0x18000
	v_bitop3_b32 v17, v15, v17, v16 bitop3:0xde
	v_lshl_add_u64 v[0:1], s[24:25], 0, v[0:1]
	v_add_u32_e32 v78, s51, v12
	s_add_i32 s51, s51, s30
	v_add_u32_e32 v80, s53, v12
	s_add_i32 s53, s53, s30
	v_lshl_add_u64 v[74:75], v[0:1], 0, s[34:35]
	s_mov_b32 s48, -2
	s_mov_b64 s[28:29], 0
	v_add_u32_e32 v79, 0, v17
	s_add_i32 s49, s1, 0xc000
	s_add_i32 s50, s1, 0xe000
	s_add_i32 s52, s51, 0x2000
	s_add_i32 s54, s53, 0x2000
	v_mov_b32_e32 v0, v69
	v_mov_b32_e32 v1, v69
	v_mov_b32_e32 v2, v69
	v_mov_b32_e32 v3, v69
	v_mov_b32_e32 v4, v69
	v_mov_b32_e32 v5, v69
	v_mov_b32_e32 v6, v69
	v_mov_b32_e32 v7, v69
	v_mov_b32_e32 v8, v69
	v_mov_b32_e32 v9, v69
	v_mov_b32_e32 v10, v69
	v_mov_b32_e32 v11, v69
	v_mov_b32_e32 v12, v69
	v_mov_b32_e32 v13, v69
	v_mov_b32_e32 v14, v69
	v_mov_b32_e32 v15, v69
	v_mov_b32_e32 v16, v69
	v_mov_b32_e32 v17, v69
	v_mov_b32_e32 v18, v69
	v_mov_b32_e32 v19, v69
	v_mov_b32_e32 v20, v69
	v_mov_b32_e32 v21, v69
	v_mov_b32_e32 v22, v69
	v_mov_b32_e32 v23, v69
	v_mov_b32_e32 v24, v69
	v_mov_b32_e32 v25, v69
	v_mov_b32_e32 v26, v69
	v_mov_b32_e32 v27, v69
	v_mov_b32_e32 v28, v69
	v_mov_b32_e32 v29, v69
	v_mov_b32_e32 v30, v69
	v_mov_b32_e32 v31, v69
	v_mov_b32_e32 v32, v69
	v_mov_b32_e32 v33, v69
	v_mov_b32_e32 v34, v69
	v_mov_b32_e32 v35, v69
	v_mov_b32_e32 v36, v69
	v_mov_b32_e32 v37, v69
	v_mov_b32_e32 v38, v69
	v_mov_b32_e32 v39, v69
	v_mov_b32_e32 v40, v69
	v_mov_b32_e32 v41, v69
	v_mov_b32_e32 v42, v69
	v_mov_b32_e32 v43, v69
	v_mov_b32_e32 v44, v69
	v_mov_b32_e32 v45, v69
	v_mov_b32_e32 v46, v69
	v_mov_b32_e32 v47, v69
	v_mov_b32_e32 v48, v69
	v_mov_b32_e32 v49, v69
	v_mov_b32_e32 v50, v69
	v_mov_b32_e32 v51, v69
	v_mov_b32_e32 v52, v69
	v_mov_b32_e32 v53, v69
	v_mov_b32_e32 v54, v69
	v_mov_b32_e32 v55, v69
	v_mov_b32_e32 v56, v69
	v_mov_b32_e32 v57, v69
	v_mov_b32_e32 v58, v69
	v_mov_b32_e32 v59, v69
	v_mov_b32_e32 v60, v69
	v_mov_b32_e32 v61, v69
	v_mov_b32_e32 v62, v69
	v_mov_b32_e32 v63, v69
	s_barrier
	s_waitcnt vmcnt(0)
	s_nop 0
	s_nop 0
	s_nop 0
	s_nop 0
	s_nop 0
	s_nop 0
	s_nop 0
	s_nop 0
	s_nop 0
	s_nop 0
	s_nop 0
	s_nop 0
	s_nop 0
	s_nop 0
	s_nop 0
	s_nop 0
	s_nop 0
	s_nop 0
	s_nop 0
	s_nop 0
	s_nop 0
	s_nop 0
	s_nop 0
	s_nop 0
	s_nop 0
	s_nop 0

; #define PG8_STAGE(bufoff, gbase, voff) do { _Pragma("unroll") for (int _i = 0; _i < 2; ++_i) \
;         __builtin_amdgcn_global_load_lds((const unsigned*)((const char*)(gbase) + (voff)[_i]), (PG8_LAS unsigned*)(lds + (bufoff) + ldsw + _i * 8192), 16, 0, 0); } while (0)
; #define PG8_WAIT_V(n) asm volatile("s_waitcnt vmcnt(" #n ")" ::: "memory")
; #define PG8_BAR __builtin_amdgcn_s_barrier()
; template <class Epi, class Sched, bool ALIGN_EPI = false, bool SP2 = false, bool MIDHOOK = false>
; __device__ __forceinline__ void gemm_phase(PG8_LAS unsigned char* lds, const Gemm g, const Sched& S, const Epi& E) {
;     ...
;     f32x4 acc[2][2][4][2];
; #pragma unroll
;     for (int a = 0; a < 2; ++a)
; #pragma unroll
;         for (int b = 0; b < 2; ++b)
; #pragma unroll
;             for (int m = 0; m < 4; ++m)
; #pragma unroll
;                 for (int n = 0; n < 2; ++n) acc[a][b][m][n] = (f32x4){0.f, 0.f, 0.f, 0.f};
;     bf16x8 At[4][2], B0[2][2], B1[2][2];
;     const char* cA = (const char*)g.A + (size_t)cur.pm * tstep; const char* cB = (const char*)g.Bt + (size_t)cur.pn * tstep;
;     S.a_ready(cur);
;     if constexpr (SP2) {
;         PG8_STAGE(PG8_SB(0, 0), cB, voffB); PG8_STAGE(PG8_SB(0, 1), cB + hstep, voffB); PG8_STAGE(PG8_SA(0, 0), cA, voffA); PG8_STAGE(PG8_SA(0, 1), cA + hstep, voffA);
;         if (wr == 1) PG8_BAR;
;         PG8_WAIT_V(2); PG8_BAR;
;         PG8_STAGE(PG8_SB(1, 0), cB + kstep, voffB); PG8_STAGE(PG8_SA(1, 0), cA + kstep, voffA); PG8_STAGE(PG8_SB(1, 1), cB + hstep + kstep, voffB);
;         PG8_WAIT_V(6); PG8_BAR;
;     } else {
;         PG8_STAGE(PG8_SB(0, 0), cB, voffB); PG8_STAGE(PG8_SA(0, 0), cA, voffA); PG8_STAGE(PG8_SB(0, 1), cB + hstep, voffB); PG8_STAGE(PG8_SA(0, 1), cA + hstep, voffA);
;         if (wr == 1) PG8_BAR;
;         PG8_WAIT_V(4); PG8_BAR;
;         PG8_STAGE(PG8_SB(1, 0), cB + kstep, voffB); PG8_STAGE(PG8_SA(1, 0), cA + kstep, voffA); PG8_STAGE(PG8_SB(1, 1), cB + hstep + kstep, voffB);
;         PG8_WAIT_V(6); PG8_BAR;
;     }
.LBB0_3911:
	s_mov_b64 s[12:13], 0x80
	s_add_i32 m0, s26, 0x18000
	v_lshl_add_u64 v[6:7], v[6:7], 0, s[12:13]
	s_and_b32 s11, s84, 3
	s_waitcnt vmcnt(2)
	s_barrier
	global_load_lds_dwordx4 v[6:7], off
	v_lshl_add_u64 v[4:5], v[4:5], 0, s[12:13]
	s_add_i32 m0, s26, 0x1a000
	s_add_i32 s31, s26, 0x8000
	s_add_i32 s33, s26, 0xa000
	global_load_lds_dwordx4 v[4:5], off
	v_lshl_add_u64 v[2:3], v[2:3], 0, s[12:13]
	s_mov_b32 m0, s31
	s_add_u32 s36, s6, 0x40080
	global_load_lds_dwordx4 v[2:3], off
	v_lshl_add_u64 v[0:1], v[0:1], 0, s[12:13]
	s_mov_b32 m0, s33
	s_addc_u32 s37, s7, 0
	global_load_lds_dwordx4 v[0:1], off
	s_add_i32 m0, s26, 0x1c000
	v_lshl_add_u64 v[0:1], s[36:37], 0, v[130:131]
	global_load_lds_dwordx4 v[0:1], off
	v_lshl_add_u64 v[0:1], s[36:37], 0, v[134:135]
	s_add_i32 m0, s26, 0x1e000
	s_add_u32 s22, s80, s22
	global_load_lds_dwordx4 v[0:1], off
	v_lshlrev_b32_e32 v0, 14, v8
	v_and_b32_e32 v0, 0xffff8000, v0
	v_lshl_add_u32 v0, v9, 11, v0
	v_and_b32_e32 v1, 1, v8
	v_lshl_or_b32 v0, v1, 6, v0
	v_lshl_add_u32 v0, v10, 1, v0
	v_mov_b32_e32 v1, v131
	s_addc_u32 s23, s81, s23
	s_mov_b64 s[34:35], 0x40080
	v_lshl_add_u64 v[0:1], s[22:23], 0, v[0:1]
	v_lshl_add_u64 v[136:137], v[0:1], 0, s[34:35]
	v_lshlrev_b32_e32 v0, 14, v11
	v_and_b32_e32 v0, 0xffff8000, v0
	v_lshl_add_u32 v0, v12, 11, v0
	v_and_b32_e32 v1, 1, v11
	v_lshl_or_b32 v0, v1, 6, v0
	v_and_b32_e32 v15, 15, v140
	v_and_b32_e32 v16, 48, v140
	v_lshl_add_u32 v0, v13, 1, v0
	v_mov_b32_e32 v1, v131
	s_add_u32 s16, s82, s16
	v_lshl_or_b32 v146, s30, 6, v15
	v_and_b32_e32 v14, 0xfffffc00, v14
	v_lshl_or_b32 v15, v15, 6, v16
	v_lshlrev_b32_e32 v16, 2, v140
	v_lshl_add_u64 v[0:1], s[22:23], 0, v[0:1]
	s_addc_u32 s17, s83, s17
	v_lshl_add_u32 v17, s30, 13, v14
	v_and_b32_e32 v16, 32, v16
	v_lshl_add_u32 v14, s11, 12, v14
	v_lshl_add_u64 v[138:139], v[0:1], 0, s[34:35]
	s_add_u32 s34, s16, 0xe00100
	v_bitop3_b32 v14, v15, v14, v16 bitop3:0xde
	s_waitcnt vmcnt(6)
	s_addc_u32 s35, s17, 0
	s_add_i32 s39, 0, 0x10000
	s_add_i32 s41, 0, 0x14000
	s_add_i32 s43, 0, 0x18000
	s_add_i32 s45, 0, 0x1c000
	v_bitop3_b32 v17, v15, v17, v16 bitop3:0xde
	v_add_u32_e32 v141, s39, v14
	v_add_u32_e32 v142, s41, v14
	s_add_i32 s39, s39, s24
	s_add_i32 s41, s41, s24
	v_add_u32_e32 v144, s43, v14
	v_add_u32_e32 v145, s45, v14
	s_add_i32 s43, s43, s24
	s_add_i32 s45, s45, s24
	s_mov_b32 s36, -2
	s_mov_b64 s[16:17], 0
	v_add_u32_e32 v143, 0, v17
	s_add_i32 s37, s26, 0xc000
	s_add_i32 s38, s26, 0xe000
	s_add_i32 s40, s39, 0x2000
	s_add_i32 s42, s41, 0x2000
	s_add_i32 s44, s43, 0x2000
	s_add_i32 s46, s45, 0x2000
	v_mov_b32_e32 v72, v131
	v_mov_b32_e32 v73, v131
	v_mov_b32_e32 v74, v131
	v_mov_b32_e32 v75, v131
	v_mov_b32_e32 v76, v131
	v_mov_b32_e32 v77, v131
	v_mov_b32_e32 v78, v131
	v_mov_b32_e32 v79, v131
	v_mov_b32_e32 v56, v131
	v_mov_b32_e32 v57, v131
	v_mov_b32_e32 v58, v131
	v_mov_b32_e32 v59, v131
	v_mov_b32_e32 v60, v131
	v_mov_b32_e32 v61, v131
	v_mov_b32_e32 v62, v131
	v_mov_b32_e32 v63, v131
	v_mov_b32_e32 v40, v131
	v_mov_b32_e32 v41, v131
	v_mov_b32_e32 v42, v131
	v_mov_b32_e32 v43, v131
	v_mov_b32_e32 v44, v131
	v_mov_b32_e32 v45, v131
	v_mov_b32_e32 v46, v131
	v_mov_b32_e32 v47, v131
	v_mov_b32_e32 v32, v131
	v_mov_b32_e32 v33, v131
	v_mov_b32_e32 v34, v131
	v_mov_b32_e32 v35, v131
	v_mov_b32_e32 v36, v131
	v_mov_b32_e32 v37, v131
	v_mov_b32_e32 v38, v131
	v_mov_b32_e32 v39, v131
	v_mov_b32_e32 v112, v131
	v_mov_b32_e32 v113, v131
	v_mov_b32_e32 v114, v131
	v_mov_b32_e32 v115, v131
	v_mov_b32_e32 v116, v131
	v_mov_b32_e32 v117, v131
	v_mov_b32_e32 v118, v131
	v_mov_b32_e32 v119, v131
	v_mov_b32_e32 v120, v131
	v_mov_b32_e32 v121, v131
	v_mov_b32_e32 v122, v131
	v_mov_b32_e32 v123, v131
	v_mov_b32_e32 v124, v131
	v_mov_b32_e32 v125, v131
	v_mov_b32_e32 v126, v131
	v_mov_b32_e32 v127, v131
	v_mov_b32_e32 v104, v131
	v_mov_b32_e32 v105, v131
	v_mov_b32_e32 v106, v131
	v_mov_b32_e32 v107, v131
	v_mov_b32_e32 v108, v131
	v_mov_b32_e32 v109, v131
	v_mov_b32_e32 v110, v131
	v_mov_b32_e32 v111, v131
	v_mov_b32_e32 v96, v131
	v_mov_b32_e32 v97, v131
	v_mov_b32_e32 v98, v131
	v_mov_b32_e32 v99, v131
	v_mov_b32_e32 v100, v131
	v_mov_b32_e32 v101, v131
	v_mov_b32_e32 v102, v131
	v_mov_b32_e32 v103, v131
	v_mov_b32_e32 v24, v131
	v_mov_b32_e32 v25, v131
	v_mov_b32_e32 v26, v131
	v_mov_b32_e32 v27, v131
	v_mov_b32_e32 v28, v131
	v_mov_b32_e32 v29, v131
	v_mov_b32_e32 v30, v131
	v_mov_b32_e32 v31, v131
	v_mov_b32_e32 v16, v131
	v_mov_b32_e32 v17, v131
	v_mov_b32_e32 v18, v131
	v_mov_b32_e32 v19, v131
	v_mov_b32_e32 v20, v131
	v_mov_b32_e32 v21, v131
	v_mov_b32_e32 v22, v131
	v_mov_b32_e32 v23, v131
	v_mov_b32_e32 v8, v131
	v_mov_b32_e32 v9, v131
	v_mov_b32_e32 v10, v131
	v_mov_b32_e32 v11, v131
	v_mov_b32_e32 v12, v131
	v_mov_b32_e32 v13, v131
	v_mov_b32_e32 v14, v131
	v_mov_b32_e32 v15, v131
	v_mov_b32_e32 v0, v131
	v_mov_b32_e32 v1, v131
	v_mov_b32_e32 v2, v131
	v_mov_b32_e32 v3, v131
	v_mov_b32_e32 v4, v131
	v_mov_b32_e32 v5, v131
	v_mov_b32_e32 v6, v131
	v_mov_b32_e32 v7, v131
	v_mov_b32_e32 v88, v131
	v_mov_b32_e32 v89, v131
	v_mov_b32_e32 v90, v131
	v_mov_b32_e32 v91, v131
	v_mov_b32_e32 v92, v131
	v_mov_b32_e32 v93, v131
	v_mov_b32_e32 v94, v131
	v_mov_b32_e32 v95, v131
	v_mov_b32_e32 v80, v131
	v_mov_b32_e32 v81, v131
	v_mov_b32_e32 v82, v131
	v_mov_b32_e32 v83, v131
	v_mov_b32_e32 v84, v131
	v_mov_b32_e32 v85, v131
	v_mov_b32_e32 v86, v131
	v_mov_b32_e32 v87, v131
	v_mov_b32_e32 v64, v131
	v_mov_b32_e32 v65, v131
	v_mov_b32_e32 v66, v131
	v_mov_b32_e32 v67, v131
	v_mov_b32_e32 v68, v131
	v_mov_b32_e32 v69, v131
	v_mov_b32_e32 v70, v131
	v_mov_b32_e32 v71, v131
	v_mov_b32_e32 v48, v131
	v_mov_b32_e32 v49, v131
	v_mov_b32_e32 v50, v131
	v_mov_b32_e32 v51, v131
	v_mov_b32_e32 v52, v131
	v_mov_b32_e32 v53, v131
	v_mov_b32_e32 v54, v131
	v_mov_b32_e32 v55, v131
	s_barrier
	s_nop 0
	s_nop 0
	s_nop 0
	s_nop 0
	s_nop 0
	s_nop 0
	s_nop 0
	s_nop 0
	s_nop 0
	s_nop 0
	s_nop 0
	s_nop 0
	s_nop 0
	s_nop 0
	s_nop 0
	s_nop 0
	s_nop 0
	s_nop 0
	s_nop 0
	s_nop 0
	s_nop 0
	s_nop 0

; #define PG8_STAGE(bufoff, gbase, voff) do { _Pragma("unroll") for (int _i = 0; _i < 2; ++_i) \
;         __builtin_amdgcn_global_load_lds((const unsigned*)((const char*)(gbase) + (voff)[_i]), (PG8_LAS unsigned*)(lds + (bufoff) + ldsw + _i * 8192), 16, 0, 0); } while (0)
; #define PG8_WAIT_V(n) asm volatile("s_waitcnt vmcnt(" #n ")" ::: "memory")
; #define PG8_BAR __builtin_amdgcn_s_barrier()
; template <class Epi, class Sched, bool ALIGN_EPI = false, bool SP2 = false, bool MIDHOOK = false>
; __device__ __forceinline__ void gemm_phase(PG8_LAS unsigned char* lds, const Gemm g, const Sched& S, const Epi& E) {
;     ...
;     f32x4 acc[2][2][4][2];
; #pragma unroll
;     for (int a = 0; a < 2; ++a)
; #pragma unroll
;         for (int b = 0; b < 2; ++b)
; #pragma unroll
;             for (int m = 0; m < 4; ++m)
; #pragma unroll
;                 for (int n = 0; n < 2; ++n) acc[a][b][m][n] = (f32x4){0.f, 0.f, 0.f, 0.f};
;     bf16x8 At[4][2], B0[2][2], B1[2][2];
;     const char* cA = (const char*)g.A + (size_t)cur.pm * tstep; const char* cB = (const char*)g.Bt + (size_t)cur.pn * tstep;
;     S.a_ready(cur);
;     if constexpr (SP2) {
;         PG8_STAGE(PG8_SB(0, 0), cB, voffB); PG8_STAGE(PG8_SB(0, 1), cB + hstep, voffB); PG8_STAGE(PG8_SA(0, 0), cA, voffA); PG8_STAGE(PG8_SA(0, 1), cA + hstep, voffA);
;         if (wr == 1) PG8_BAR;
;         PG8_WAIT_V(2); PG8_BAR;
;         PG8_STAGE(PG8_SB(1, 0), cB + kstep, voffB); PG8_STAGE(PG8_SA(1, 0), cA + kstep, voffA); PG8_STAGE(PG8_SB(1, 1), cB + hstep + kstep, voffB);
;         PG8_WAIT_V(6); PG8_BAR;
;     } else {
;         PG8_STAGE(PG8_SB(0, 0), cB, voffB); PG8_STAGE(PG8_SA(0, 0), cA, voffA); PG8_STAGE(PG8_SB(0, 1), cB + hstep, voffB); PG8_STAGE(PG8_SA(0, 1), cA + hstep, voffA);
;         if (wr == 1) PG8_BAR;
;         PG8_WAIT_V(4); PG8_BAR;
;         PG8_STAGE(PG8_SB(1, 0), cB + kstep, voffB); PG8_STAGE(PG8_SA(1, 0), cA + kstep, voffA); PG8_STAGE(PG8_SB(1, 1), cB + hstep + kstep, voffB);
;         PG8_WAIT_V(6); PG8_BAR;
;     }
.LBB0_4174:
	s_mov_b64 s[8:9], 0x80
	s_add_i32 m0, s30, 0x18000
	v_lshl_add_u64 v[6:7], v[6:7], 0, s[8:9]
	s_and_b32 s3, s84, 3
	s_waitcnt vmcnt(2)
	s_barrier
	global_load_lds_dwordx4 v[6:7], off
	v_lshl_add_u64 v[4:5], v[4:5], 0, s[8:9]
	s_add_i32 m0, s30, 0x1a000
	s_add_i32 s35, s30, 0x8000
	s_add_i32 s36, s30, 0xa000
	global_load_lds_dwordx4 v[4:5], off
	v_lshl_add_u64 v[2:3], v[2:3], 0, s[8:9]
	s_mov_b32 m0, s35
	s_add_u32 s28, s0, 0x100080
	global_load_lds_dwordx4 v[2:3], off
	v_lshl_add_u64 v[0:1], v[0:1], 0, s[8:9]
	s_mov_b32 m0, s36
	s_addc_u32 s29, s1, 0
	global_load_lds_dwordx4 v[0:1], off
	s_add_i32 m0, s30, 0x1c000
	v_lshl_add_u64 v[0:1], s[28:29], 0, v[130:131]
	global_load_lds_dwordx4 v[0:1], off
	v_lshl_add_u64 v[0:1], s[28:29], 0, v[134:135]
	s_add_i32 m0, s30, 0x1e000
	s_add_u32 s22, s82, s22
	global_load_lds_dwordx4 v[0:1], off
	v_lshlrev_b32_e32 v0, 16, v8
	v_and_b32_e32 v0, 0xfffe0000, v0
	v_lshl_add_u32 v0, v9, 13, v0
	v_and_b32_e32 v1, 1, v8
	v_lshl_or_b32 v0, v1, 6, v0
	s_addc_u32 s23, s83, s23
	v_lshl_add_u32 v0, v10, 1, v0
	v_mov_b32_e32 v1, v131
	v_lshl_add_u64 v[0:1], s[22:23], 0, v[0:1]
	s_mov_b64 s[28:29], 0xe100080
	v_lshl_add_u64 v[136:137], v[0:1], 0, s[28:29]
	v_lshlrev_b32_e32 v0, 16, v11
	v_and_b32_e32 v15, 15, v140
	v_and_b32_e32 v16, 48, v140
	v_and_b32_e32 v0, 0xfffe0000, v0
	s_add_u32 s24, s82, s24
	v_lshl_or_b32 v146, s17, 6, v15
	v_and_b32_e32 v14, 0xfffffc00, v14
	v_lshl_or_b32 v15, v15, 6, v16
	v_lshlrev_b32_e32 v16, 2, v140
	v_lshl_add_u32 v0, v12, 13, v0
	v_and_b32_e32 v1, 1, v11
	s_addc_u32 s25, s83, s25
	v_lshl_add_u32 v17, s17, 13, v14
	v_and_b32_e32 v16, 32, v16
	v_lshl_add_u32 v14, s3, 12, v14
	v_lshl_or_b32 v0, v1, 6, v0
	s_add_u32 s37, s24, 0x1800100
	v_bitop3_b32 v14, v15, v14, v16 bitop3:0xde
	s_waitcnt vmcnt(6)
	v_lshl_add_u32 v0, v13, 1, v0
	v_mov_b32_e32 v1, v131
	s_addc_u32 s38, s25, 0
	s_add_i32 s42, 0, 0x10000
	s_add_i32 s44, 0, 0x14000
	s_add_i32 s46, 0, 0x18000
	s_add_i32 s48, 0, 0x1c000
	v_bitop3_b32 v17, v15, v17, v16 bitop3:0xde
	v_lshl_add_u64 v[0:1], s[22:23], 0, v[0:1]
	v_add_u32_e32 v141, s42, v14
	v_add_u32_e32 v142, s44, v14
	s_add_i32 s42, s42, s26
	s_add_i32 s44, s44, s26
	v_add_u32_e32 v144, s46, v14
	v_add_u32_e32 v145, s48, v14
	s_add_i32 s46, s46, s26
	s_add_i32 s48, s48, s26
	v_lshl_add_u64 v[138:139], v[0:1], 0, s[28:29]
	s_mov_b32 s39, -2
	s_mov_b64 s[24:25], 0
	v_add_u32_e32 v143, 0, v17
	s_add_i32 s40, s30, 0xc000
	s_add_i32 s41, s30, 0xe000
	s_add_i32 s43, s42, 0x2000
	s_add_i32 s45, s44, 0x2000
	s_add_i32 s47, s46, 0x2000
	s_add_i32 s49, s48, 0x2000
	v_mov_b32_e32 v72, v131
	v_mov_b32_e32 v73, v131
	v_mov_b32_e32 v74, v131
	v_mov_b32_e32 v75, v131
	v_mov_b32_e32 v76, v131
	v_mov_b32_e32 v77, v131
	v_mov_b32_e32 v78, v131
	v_mov_b32_e32 v79, v131
	v_mov_b32_e32 v56, v131
	v_mov_b32_e32 v57, v131
	v_mov_b32_e32 v58, v131
	v_mov_b32_e32 v59, v131
	v_mov_b32_e32 v60, v131
	v_mov_b32_e32 v61, v131
	v_mov_b32_e32 v62, v131
	v_mov_b32_e32 v63, v131
	v_mov_b32_e32 v40, v131
	v_mov_b32_e32 v41, v131
	v_mov_b32_e32 v42, v131
	v_mov_b32_e32 v43, v131
	v_mov_b32_e32 v44, v131
	v_mov_b32_e32 v45, v131
	v_mov_b32_e32 v46, v131
	v_mov_b32_e32 v47, v131
	v_mov_b32_e32 v32, v131
	v_mov_b32_e32 v33, v131
	v_mov_b32_e32 v34, v131
	v_mov_b32_e32 v35, v131
	v_mov_b32_e32 v36, v131
	v_mov_b32_e32 v37, v131
	v_mov_b32_e32 v38, v131
	v_mov_b32_e32 v39, v131
	v_mov_b32_e32 v116, v131
	v_mov_b32_e32 v117, v131
	v_mov_b32_e32 v118, v131
	v_mov_b32_e32 v119, v131
	v_mov_b32_e32 v120, v131
	v_mov_b32_e32 v121, v131
	v_mov_b32_e32 v122, v131
	v_mov_b32_e32 v123, v131
	v_mov_b32_e32 v112, v131
	v_mov_b32_e32 v113, v131
	v_mov_b32_e32 v114, v131
	v_mov_b32_e32 v115, v131
	v_mov_b32_e32 v124, v131
	v_mov_b32_e32 v125, v131
	v_mov_b32_e32 v126, v131
	v_mov_b32_e32 v127, v131
	v_mov_b32_e32 v104, v131
	v_mov_b32_e32 v105, v131
	v_mov_b32_e32 v106, v131
	v_mov_b32_e32 v107, v131
	v_mov_b32_e32 v108, v131
	v_mov_b32_e32 v109, v131
	v_mov_b32_e32 v110, v131
	v_mov_b32_e32 v111, v131
	v_mov_b32_e32 v96, v131
	v_mov_b32_e32 v97, v131
	v_mov_b32_e32 v98, v131
	v_mov_b32_e32 v99, v131
	v_mov_b32_e32 v100, v131
	v_mov_b32_e32 v101, v131
	v_mov_b32_e32 v102, v131
	v_mov_b32_e32 v103, v131
	v_mov_b32_e32 v24, v131
	v_mov_b32_e32 v25, v131
	v_mov_b32_e32 v26, v131
	v_mov_b32_e32 v27, v131
	v_mov_b32_e32 v28, v131
	v_mov_b32_e32 v29, v131
	v_mov_b32_e32 v30, v131
	v_mov_b32_e32 v31, v131
	v_mov_b32_e32 v16, v131
	v_mov_b32_e32 v17, v131
	v_mov_b32_e32 v18, v131
	v_mov_b32_e32 v19, v131
	v_mov_b32_e32 v20, v131
	v_mov_b32_e32 v21, v131
	v_mov_b32_e32 v22, v131
	v_mov_b32_e32 v23, v131
	v_mov_b32_e32 v8, v131
	v_mov_b32_e32 v9, v131
	v_mov_b32_e32 v10, v131
	v_mov_b32_e32 v11, v131
	v_mov_b32_e32 v12, v131
	v_mov_b32_e32 v13, v131
	v_mov_b32_e32 v14, v131
	v_mov_b32_e32 v15, v131
	v_mov_b32_e32 v0, v131
	v_mov_b32_e32 v1, v131
	v_mov_b32_e32 v2, v131
	v_mov_b32_e32 v3, v131
	v_mov_b32_e32 v4, v131
	v_mov_b32_e32 v5, v131
	v_mov_b32_e32 v6, v131
	v_mov_b32_e32 v7, v131
	v_mov_b32_e32 v88, v131
	v_mov_b32_e32 v89, v131
	v_mov_b32_e32 v90, v131
	v_mov_b32_e32 v91, v131
	v_mov_b32_e32 v92, v131
	v_mov_b32_e32 v93, v131
	v_mov_b32_e32 v94, v131
	v_mov_b32_e32 v95, v131
	v_mov_b32_e32 v80, v131
	v_mov_b32_e32 v81, v131
	v_mov_b32_e32 v82, v131
	v_mov_b32_e32 v83, v131
	v_mov_b32_e32 v84, v131
	v_mov_b32_e32 v85, v131
	v_mov_b32_e32 v86, v131
	v_mov_b32_e32 v87, v131
	v_mov_b32_e32 v64, v131
	v_mov_b32_e32 v65, v131
	v_mov_b32_e32 v66, v131
	v_mov_b32_e32 v67, v131
	v_mov_b32_e32 v68, v131
	v_mov_b32_e32 v69, v131
	v_mov_b32_e32 v70, v131
	v_mov_b32_e32 v71, v131
	v_mov_b32_e32 v48, v131
	v_mov_b32_e32 v49, v131
	v_mov_b32_e32 v50, v131
	v_mov_b32_e32 v51, v131
	v_mov_b32_e32 v52, v131
	v_mov_b32_e32 v53, v131
	v_mov_b32_e32 v54, v131
	v_mov_b32_e32 v55, v131
	s_barrier
	s_nop 0
	s_nop 0
	s_nop 0
	s_nop 0
	s_nop 0
	s_nop 0
	s_nop 0
	s_nop 0
	s_nop 0
	s_nop 0
	s_nop 0
	s_nop 0
	s_nop 0
	s_nop 0
	s_nop 0
	s_nop 0
	s_nop 0
	s_nop 0
	s_nop 0
	s_nop 0

; #define PG8_STAGE(bufoff, gbase, voff) do { _Pragma("unroll") for (int _i = 0; _i < 2; ++_i) \
;         __builtin_amdgcn_global_load_lds((const unsigned*)((const char*)(gbase) + (voff)[_i]), (PG8_LAS unsigned*)(lds + (bufoff) + ldsw + _i * 8192), 16, 0, 0); } while (0)
; #define PG8_WAIT_V(n) asm volatile("s_waitcnt vmcnt(" #n ")" ::: "memory")
; #define PG8_BAR __builtin_amdgcn_s_barrier()
; template <class Epi, class Sched, bool ALIGN_EPI = false, bool SP2 = false, bool MIDHOOK = false>
; __device__ __forceinline__ void gemm_phase(PG8_LAS unsigned char* lds, const Gemm g, const Sched& S, const Epi& E) {
;     ...
;     f32x4 acc[2][2][4][2];
; #pragma unroll
;     for (int a = 0; a < 2; ++a)
; #pragma unroll
;         for (int b = 0; b < 2; ++b)
; #pragma unroll
;             for (int m = 0; m < 4; ++m)
; #pragma unroll
;                 for (int n = 0; n < 2; ++n) acc[a][b][m][n] = (f32x4){0.f, 0.f, 0.f, 0.f};
;     bf16x8 At[4][2], B0[2][2], B1[2][2];
;     const char* cA = (const char*)g.A + (size_t)cur.pm * tstep; const char* cB = (const char*)g.Bt + (size_t)cur.pn * tstep;
;     S.a_ready(cur);
;     if constexpr (SP2) {
;         PG8_STAGE(PG8_SB(0, 0), cB, voffB); PG8_STAGE(PG8_SB(0, 1), cB + hstep, voffB); PG8_STAGE(PG8_SA(0, 0), cA, voffA); PG8_STAGE(PG8_SA(0, 1), cA + hstep, voffA);
;         if (wr == 1) PG8_BAR;
;         PG8_WAIT_V(2); PG8_BAR;
;         PG8_STAGE(PG8_SB(1, 0), cB + kstep, voffB); PG8_STAGE(PG8_SA(1, 0), cA + kstep, voffA); PG8_STAGE(PG8_SB(1, 1), cB + hstep + kstep, voffB);
;         PG8_WAIT_V(6); PG8_BAR;
;     } else {
;         PG8_STAGE(PG8_SB(0, 0), cB, voffB); PG8_STAGE(PG8_SA(0, 0), cA, voffA); PG8_STAGE(PG8_SB(0, 1), cB + hstep, voffB); PG8_STAGE(PG8_SA(0, 1), cA + hstep, voffA);
;         if (wr == 1) PG8_BAR;
;         PG8_WAIT_V(4); PG8_BAR;
;         PG8_STAGE(PG8_SB(1, 0), cB + kstep, voffB); PG8_STAGE(PG8_SA(1, 0), cA + kstep, voffA); PG8_STAGE(PG8_SB(1, 1), cB + hstep + kstep, voffB);
;         PG8_WAIT_V(6); PG8_BAR;
;     }
.LBB0_4241:
	s_mov_b64 s[8:9], 0x80
	s_add_i32 m0, s25, 0x18000
	v_lshl_add_u64 v[6:7], v[6:7], 0, s[8:9]
	s_and_b32 s7, s84, 3
	s_waitcnt vmcnt(2)
	s_barrier
	global_load_lds_dwordx4 v[6:7], off
	v_lshl_add_u64 v[4:5], v[4:5], 0, s[8:9]
	s_add_i32 m0, s25, 0x1a000
	s_add_i32 s29, s25, 0x8000
	s_add_i32 s30, s25, 0xa000
	global_load_lds_dwordx4 v[4:5], off
	v_lshl_add_u64 v[2:3], v[2:3], 0, s[8:9]
	s_mov_b32 m0, s29
	s_add_u32 s20, s0, 0x100080
	global_load_lds_dwordx4 v[2:3], off
	v_lshl_add_u64 v[0:1], v[0:1], 0, s[8:9]
	s_mov_b32 m0, s30
	s_addc_u32 s21, s1, 0
	global_load_lds_dwordx4 v[0:1], off
	s_add_i32 m0, s25, 0x1c000
	v_lshl_add_u64 v[0:1], s[20:21], 0, v[130:131]
	global_load_lds_dwordx4 v[0:1], off
	v_lshl_add_u64 v[0:1], s[20:21], 0, v[134:135]
	s_add_i32 m0, s25, 0x1e000
	s_add_u32 s12, s82, s12
	global_load_lds_dwordx4 v[0:1], off
	v_lshlrev_b32_e32 v0, 16, v8
	v_and_b32_e32 v0, 0xfffe0000, v0
	v_lshl_add_u32 v0, v9, 13, v0
	v_and_b32_e32 v1, 1, v8
	v_lshl_or_b32 v0, v1, 6, v0
	s_addc_u32 s13, s83, s13
	v_lshl_add_u32 v0, v10, 1, v0
	v_mov_b32_e32 v1, v131
	v_lshl_add_u64 v[0:1], s[12:13], 0, v[0:1]
	s_mov_b64 s[20:21], 0xe100080
	v_lshl_add_u64 v[136:137], v[0:1], 0, s[20:21]
	v_lshlrev_b32_e32 v0, 16, v11
	v_and_b32_e32 v15, 15, v220
	v_and_b32_e32 v16, 48, v220
	v_and_b32_e32 v0, 0xfffe0000, v0
	s_add_u32 s16, s82, s16
	v_lshl_or_b32 v146, s24, 6, v15
	v_and_b32_e32 v14, 0xfffffc00, v14
	v_lshl_or_b32 v15, v15, 6, v16
	v_lshlrev_b32_e32 v16, 2, v220
	v_lshl_add_u32 v0, v12, 13, v0
	v_and_b32_e32 v1, 1, v11
	s_addc_u32 s17, s83, s17
	v_lshl_add_u32 v17, s24, 13, v14
	v_and_b32_e32 v16, 32, v16
	v_lshl_add_u32 v14, s7, 12, v14
	v_lshl_or_b32 v0, v1, 6, v0
	s_add_u32 s31, s16, 0x1800100
	v_bitop3_b32 v14, v15, v14, v16 bitop3:0xde
	s_waitcnt vmcnt(6)
	v_lshl_add_u32 v0, v13, 1, v0
	v_mov_b32_e32 v1, v131
	s_addc_u32 s33, s17, 0
	s_add_i32 s37, 0, 0x10000
	s_add_i32 s39, 0, 0x14000
	s_add_i32 s41, 0, 0x18000
	s_add_i32 s43, 0, 0x1c000
	v_bitop3_b32 v17, v15, v17, v16 bitop3:0xde
	v_lshl_add_u64 v[0:1], s[12:13], 0, v[0:1]
	v_add_u32_e32 v140, s37, v14
	v_add_u32_e32 v141, s39, v14
	s_add_i32 s37, s37, s22
	s_add_i32 s39, s39, s22
	v_add_u32_e32 v143, s41, v14
	v_add_u32_e32 v144, s43, v14
	s_add_i32 s41, s41, s22
	s_add_i32 s43, s43, s22
	v_lshl_add_u64 v[138:139], v[0:1], 0, s[20:21]
	s_mov_b32 s34, -2
	s_mov_b64 s[16:17], 0
	v_add_u32_e32 v142, 0, v17
	s_add_i32 s35, s25, 0xc000
	s_add_i32 s36, s25, 0xe000
	s_add_i32 s38, s37, 0x2000
	s_add_i32 s40, s39, 0x2000
	s_add_i32 s42, s41, 0x2000
	s_add_i32 s44, s43, 0x2000
	v_mov_b32_e32 v72, v131
	v_mov_b32_e32 v73, v131
	v_mov_b32_e32 v74, v131
	v_mov_b32_e32 v75, v131
	v_mov_b32_e32 v76, v131
	v_mov_b32_e32 v77, v131
	v_mov_b32_e32 v78, v131
	v_mov_b32_e32 v79, v131
	v_mov_b32_e32 v56, v131
	v_mov_b32_e32 v57, v131
	v_mov_b32_e32 v58, v131
	v_mov_b32_e32 v59, v131
	v_mov_b32_e32 v60, v131
	v_mov_b32_e32 v61, v131
	v_mov_b32_e32 v62, v131
	v_mov_b32_e32 v63, v131
	v_mov_b32_e32 v40, v131
	v_mov_b32_e32 v41, v131
	v_mov_b32_e32 v42, v131
	v_mov_b32_e32 v43, v131
	v_mov_b32_e32 v44, v131
	v_mov_b32_e32 v45, v131
	v_mov_b32_e32 v46, v131
	v_mov_b32_e32 v47, v131
	v_mov_b32_e32 v32, v131
	v_mov_b32_e32 v33, v131
	v_mov_b32_e32 v34, v131
	v_mov_b32_e32 v35, v131
	v_mov_b32_e32 v36, v131
	v_mov_b32_e32 v37, v131
	v_mov_b32_e32 v38, v131
	v_mov_b32_e32 v39, v131
	v_mov_b32_e32 v116, v131
	v_mov_b32_e32 v117, v131
	v_mov_b32_e32 v118, v131
	v_mov_b32_e32 v119, v131
	v_mov_b32_e32 v120, v131
	v_mov_b32_e32 v121, v131
	v_mov_b32_e32 v122, v131
	v_mov_b32_e32 v123, v131
	v_mov_b32_e32 v112, v131
	v_mov_b32_e32 v113, v131
	v_mov_b32_e32 v114, v131
	v_mov_b32_e32 v115, v131
	v_mov_b32_e32 v124, v131
	v_mov_b32_e32 v125, v131
	v_mov_b32_e32 v126, v131
	v_mov_b32_e32 v127, v131
	v_mov_b32_e32 v104, v131
	v_mov_b32_e32 v105, v131
	v_mov_b32_e32 v106, v131
	v_mov_b32_e32 v107, v131
	v_mov_b32_e32 v108, v131
	v_mov_b32_e32 v109, v131
	v_mov_b32_e32 v110, v131
	v_mov_b32_e32 v111, v131
	v_mov_b32_e32 v96, v131
	v_mov_b32_e32 v97, v131
	v_mov_b32_e32 v98, v131
	v_mov_b32_e32 v99, v131
	v_mov_b32_e32 v100, v131
	v_mov_b32_e32 v101, v131
	v_mov_b32_e32 v102, v131
	v_mov_b32_e32 v103, v131
	v_mov_b32_e32 v24, v131
	v_mov_b32_e32 v25, v131
	v_mov_b32_e32 v26, v131
	v_mov_b32_e32 v27, v131
	v_mov_b32_e32 v28, v131
	v_mov_b32_e32 v29, v131
	v_mov_b32_e32 v30, v131
	v_mov_b32_e32 v31, v131
	v_mov_b32_e32 v16, v131
	v_mov_b32_e32 v17, v131
	v_mov_b32_e32 v18, v131
	v_mov_b32_e32 v19, v131
	v_mov_b32_e32 v20, v131
	v_mov_b32_e32 v21, v131
	v_mov_b32_e32 v22, v131
	v_mov_b32_e32 v23, v131
	v_mov_b32_e32 v8, v131
	v_mov_b32_e32 v9, v131
	v_mov_b32_e32 v10, v131
	v_mov_b32_e32 v11, v131
	v_mov_b32_e32 v12, v131
	v_mov_b32_e32 v13, v131
	v_mov_b32_e32 v14, v131
	v_mov_b32_e32 v15, v131
	v_mov_b32_e32 v0, v131
	v_mov_b32_e32 v1, v131
	v_mov_b32_e32 v2, v131
	v_mov_b32_e32 v3, v131
	v_mov_b32_e32 v4, v131
	v_mov_b32_e32 v5, v131
	v_mov_b32_e32 v6, v131
	v_mov_b32_e32 v7, v131
	v_mov_b32_e32 v88, v131
	v_mov_b32_e32 v89, v131
	v_mov_b32_e32 v90, v131
	v_mov_b32_e32 v91, v131
	v_mov_b32_e32 v92, v131
	v_mov_b32_e32 v93, v131
	v_mov_b32_e32 v94, v131
	v_mov_b32_e32 v95, v131
	v_mov_b32_e32 v80, v131
	v_mov_b32_e32 v81, v131
	v_mov_b32_e32 v82, v131
	v_mov_b32_e32 v83, v131
	v_mov_b32_e32 v84, v131
	v_mov_b32_e32 v85, v131
	v_mov_b32_e32 v86, v131
	v_mov_b32_e32 v87, v131
	v_mov_b32_e32 v64, v131
	v_mov_b32_e32 v65, v131
	v_mov_b32_e32 v66, v131
	v_mov_b32_e32 v67, v131
	v_mov_b32_e32 v68, v131
	v_mov_b32_e32 v69, v131
	v_mov_b32_e32 v70, v131
	v_mov_b32_e32 v71, v131
	v_mov_b32_e32 v48, v131
	v_mov_b32_e32 v49, v131
	v_mov_b32_e32 v50, v131
	v_mov_b32_e32 v51, v131
	v_mov_b32_e32 v52, v131
	v_mov_b32_e32 v53, v131
	v_mov_b32_e32 v54, v131
	v_mov_b32_e32 v55, v131
	s_barrier
	s_nop 0
	s_nop 0
	s_nop 0
	s_nop 0
	s_nop 0
	s_nop 0
	s_nop 0
	s_nop 0
	s_nop 0
	s_nop 0
	s_nop 0
	s_nop 0
	s_nop 0
	s_nop 0
	s_nop 0
	s_nop 0
